# phase-4 attention loop rewritten like phase-3 (frag prefetch, trimmed VALU, interleaved PV)
# speedup vs baseline: 1.0290x; 1.0019x over previous
.LBB0_902:
	s_add_i32 s36, s37, 1
	v_cmp_lt_i32_e32 vcc, s37, v130
	s_and_saveexec_b64 s[22:23], vcc
	s_cbranch_execz .LBB0_904
	s_bitcmp1_b32 s36, 0
	s_cselect_b32 s38, 0x4800, 0
	v_add_u32_e32 v0, s38, v163
	s_waitcnt vmcnt(1)
	ds_write_b128 v0, v[48:51]
	ds_write_b128 v0, v[52:55] offset:9216
.LBB0_904:
	s_or_b64 exec, exec, s[22:23]
	s_add_i32 s22, s37, 3
	v_min_i32_e32 v0, s22, v130
	v_lshlrev_b32_e32 v0, 6, v0
	v_add_u32_e32 v2, v0, v162
	s_bitcmp1_b32 s37, 0
	s_mov_b32 s22, 0x23800
	v_ashrrev_i32_e32 v3, 31, v2
	s_cselect_b32 s22, s22, 0x1f000
	v_lshlrev_b64 v[2:3], 7, v[2:3]
	v_lshl_add_u64 v[6:7], v[0:1], 1, v[126:127]
	v_or_b32_e32 v0, s22, v124
	v_lshl_add_u64 v[2:3], v[128:129], 0, v[2:3]
	v_add_u32_e32 v0, v0, v131
	global_load_dwordx4 v[2:5], v[2:3], off
	s_nop 0
	global_load_dwordx4 v[6:9], v[6:7], off
	ds_read_b128 v[200:203], v0
	ds_read_b128 v[204:207], v0 offset:32
	ds_read_b128 v[208:211], v0 offset:64
	ds_read_b128 v[212:215], v0 offset:96
	ds_read_b128 v[216:219], v0 offset:4608
	ds_read_b128 v[220:223], v0 offset:4640
	ds_read_b128 v[224:227], v0 offset:4672
	ds_read_b128 v[228:231], v0 offset:4704
	ds_read_b64 v[232:233], v132
	v_lshlrev_b32_e32 v0, 1, v125
	v_add3_u32 v0, s22, v131, v0
	v_add_u32_e32 v13, 0x2000, v0
	v_add_u32_e32 v0, 0x3000, v0
	s_waitcnt vmcnt(3)
	s_waitcnt lgkmcnt(8)
	v_mfma_f32_32x32x16_bf16 v[64:79], v[200:203], v[92:95], 0
	s_waitcnt lgkmcnt(7)
	v_mfma_f32_32x32x16_bf16 v[64:79], v[204:207], v[80:83], v[64:79]
	s_waitcnt lgkmcnt(6)
	v_mfma_f32_32x32x16_bf16 v[64:79], v[208:211], v[84:87], v[64:79]
	s_waitcnt lgkmcnt(5)
	v_mfma_f32_32x32x16_bf16 v[64:79], v[212:215], v[88:91], v[64:79]
	s_waitcnt lgkmcnt(4)
	v_mfma_f32_32x32x16_bf16 v[48:63], v[216:219], v[92:95], 0
	s_waitcnt lgkmcnt(3)
	v_mfma_f32_32x32x16_bf16 v[48:63], v[220:223], v[80:83], v[48:63]
	s_waitcnt lgkmcnt(2)
	v_mfma_f32_32x32x16_bf16 v[48:63], v[224:227], v[84:87], v[48:63]
	s_waitcnt lgkmcnt(1)
	v_mfma_f32_32x32x16_bf16 v[48:63], v[228:231], v[88:91], v[48:63]
	ds_read2_b64 v[200:203], v13 offset0:128 offset1:130
	ds_read2_b64 v[216:219], v0 offset0:192 offset1:194
	ds_read2_b64 v[204:207], v13 offset0:132 offset1:134
	ds_read2_b64 v[220:223], v0 offset0:196 offset1:198
	ds_read2_b64 v[208:211], v13 offset0:136 offset1:138
	ds_read2_b64 v[224:227], v0 offset0:200 offset1:202
	ds_read2_b64 v[212:215], v13 offset0:140 offset1:142
	ds_read2_b64 v[228:231], v0 offset0:204 offset1:206
	v_max3_f32 v254, v64, v65, v66
	v_max3_f32 v254, v254, v67, v68
	v_max3_f32 v254, v254, v69, v70
	v_max3_f32 v254, v254, v71, v72
	v_max3_f32 v254, v254, v73, v74
	v_max3_f32 v254, v254, v75, v76
	v_max3_f32 v254, v254, v77, v78
	v_max_f32_e32 v254, v254, v79
	v_max3_f32 v255, v48, v49, v50
	v_max3_f32 v255, v255, v51, v52
	v_max3_f32 v255, v255, v53, v54
	v_max3_f32 v255, v255, v55, v56
	v_max3_f32 v255, v255, v57, v58
	v_max3_f32 v255, v255, v59, v60
	v_max3_f32 v255, v255, v61, v62
	v_max_f32_e32 v255, v255, v63
	v_max_f32_e32 v254, v254, v255
	ds_bpermute_b32 v12, v234, v254
	v_mov_b32_e32 v10, 0
	s_waitcnt lgkmcnt(0)
	v_max3_f32 v12, v135, v254, v12
	v_sub_f32_e32 v250, v135, v12
	v_exp_f32_e32 v250, v250
	v_cmp_neq_f32_e32 vcc, v12, v135
	v_lshrrev_b32_e32 v232, v125, v232
	v_lshrrev_b32_e32 v233, v125, v233
	s_cbranch_vccz .Lattn4_nors
	v_pk_mul_f32 v[46:47], v[46:47], v[250:251] op_sel_hi:[1,0]
	v_pk_mul_f32 v[44:45], v[44:45], v[250:251] op_sel_hi:[1,0]
	v_pk_mul_f32 v[42:43], v[42:43], v[250:251] op_sel_hi:[1,0]
	v_pk_mul_f32 v[40:41], v[40:41], v[250:251] op_sel_hi:[1,0]
	v_pk_mul_f32 v[38:39], v[38:39], v[250:251] op_sel_hi:[1,0]
	v_pk_mul_f32 v[36:37], v[36:37], v[250:251] op_sel_hi:[1,0]
	v_pk_mul_f32 v[34:35], v[34:35], v[250:251] op_sel_hi:[1,0]
	v_pk_mul_f32 v[32:33], v[32:33], v[250:251] op_sel_hi:[1,0]
	v_pk_mul_f32 v[30:31], v[30:31], v[250:251] op_sel_hi:[1,0]
	v_pk_mul_f32 v[28:29], v[28:29], v[250:251] op_sel_hi:[1,0]
	v_pk_mul_f32 v[26:27], v[26:27], v[250:251] op_sel_hi:[1,0]
	v_pk_mul_f32 v[24:25], v[24:25], v[250:251] op_sel_hi:[1,0]
	v_pk_mul_f32 v[22:23], v[22:23], v[250:251] op_sel_hi:[1,0]
	v_pk_mul_f32 v[20:21], v[20:21], v[250:251] op_sel_hi:[1,0]
	v_pk_mul_f32 v[18:19], v[18:19], v[250:251] op_sel_hi:[1,0]
	v_pk_mul_f32 v[16:17], v[16:17], v[250:251] op_sel_hi:[1,0]
.Lattn4_nors:
	v_sub_f32_e32 v64, v64, v12
	v_sub_f32_e32 v65, v65, v12
	v_exp_f32_e32 v64, v64
	v_exp_f32_e32 v65, v65
	v_bfe_i32 v199, v232, 0, 1
	v_bfe_i32 v241, v232, 1, 1
	v_and_b32_e32 v64, v64, v199
	v_and_b32_e32 v65, v65, v241
	v_add_f32_e32 v10, v64, v10
	v_add_f32_e32 v10, v65, v10
	v_cvt_pk_bf16_f32 v242, v64, v65
	v_sub_f32_e32 v66, v66, v12
	v_sub_f32_e32 v67, v67, v12
	v_exp_f32_e32 v66, v66
	v_exp_f32_e32 v67, v67
	v_bfe_i32 v199, v232, 2, 1
	v_bfe_i32 v241, v232, 3, 1
	v_and_b32_e32 v66, v66, v199
	v_and_b32_e32 v67, v67, v241
	v_add_f32_e32 v10, v66, v10
	v_add_f32_e32 v10, v67, v10
	v_cvt_pk_bf16_f32 v243, v66, v67
	v_sub_f32_e32 v68, v68, v12
	v_sub_f32_e32 v69, v69, v12
	v_exp_f32_e32 v68, v68
	v_exp_f32_e32 v69, v69
	v_bfe_i32 v199, v232, 8, 1
	v_bfe_i32 v241, v232, 9, 1
	v_and_b32_e32 v68, v68, v199
	v_and_b32_e32 v69, v69, v241
	v_add_f32_e32 v10, v68, v10
	v_add_f32_e32 v10, v69, v10
	v_cvt_pk_bf16_f32 v244, v68, v69
	v_sub_f32_e32 v70, v70, v12
	v_sub_f32_e32 v71, v71, v12
	v_exp_f32_e32 v70, v70
	v_exp_f32_e32 v71, v71
	v_bfe_i32 v199, v232, 10, 1
	v_bfe_i32 v241, v232, 11, 1
	v_and_b32_e32 v70, v70, v199
	v_and_b32_e32 v71, v71, v241
	v_add_f32_e32 v10, v70, v10
	v_add_f32_e32 v10, v71, v10
	v_cvt_pk_bf16_f32 v245, v70, v71
	v_sub_f32_e32 v72, v72, v12
	v_sub_f32_e32 v73, v73, v12
	v_exp_f32_e32 v72, v72
	v_exp_f32_e32 v73, v73
	v_bfe_i32 v199, v232, 16, 1
	v_bfe_i32 v241, v232, 17, 1
	v_and_b32_e32 v72, v72, v199
	v_and_b32_e32 v73, v73, v241
	v_add_f32_e32 v10, v72, v10
	v_add_f32_e32 v10, v73, v10
	v_cvt_pk_bf16_f32 v246, v72, v73
	v_mfma_f32_32x32x16_bf16 v[32:47], v[200:203], v[242:245], v[32:47]
	v_sub_f32_e32 v74, v74, v12
	v_sub_f32_e32 v75, v75, v12
	v_exp_f32_e32 v74, v74
	v_exp_f32_e32 v75, v75
	v_bfe_i32 v199, v232, 18, 1
	v_bfe_i32 v241, v232, 19, 1
	v_and_b32_e32 v74, v74, v199
	v_and_b32_e32 v75, v75, v241
	v_add_f32_e32 v10, v74, v10
	v_add_f32_e32 v10, v75, v10
	v_cvt_pk_bf16_f32 v247, v74, v75
	v_sub_f32_e32 v76, v76, v12
	v_sub_f32_e32 v77, v77, v12
	v_exp_f32_e32 v76, v76
	v_exp_f32_e32 v77, v77
	v_bfe_i32 v199, v232, 24, 1
	v_bfe_i32 v241, v232, 25, 1
	v_and_b32_e32 v76, v76, v199
	v_and_b32_e32 v77, v77, v241
	v_add_f32_e32 v10, v76, v10
	v_add_f32_e32 v10, v77, v10
	v_cvt_pk_bf16_f32 v248, v76, v77
	v_mfma_f32_32x32x16_bf16 v[16:31], v[216:219], v[242:245], v[16:31]
	v_sub_f32_e32 v78, v78, v12
	v_sub_f32_e32 v79, v79, v12
	v_exp_f32_e32 v78, v78
	v_exp_f32_e32 v79, v79
	v_bfe_i32 v199, v232, 26, 1
	v_bfe_i32 v241, v232, 27, 1
	v_and_b32_e32 v78, v78, v199
	v_and_b32_e32 v79, v79, v241
	v_add_f32_e32 v10, v78, v10
	v_add_f32_e32 v10, v79, v10
	v_cvt_pk_bf16_f32 v249, v78, v79
	v_sub_f32_e32 v48, v48, v12
	v_sub_f32_e32 v49, v49, v12
	v_exp_f32_e32 v48, v48
	v_exp_f32_e32 v49, v49
	v_bfe_i32 v199, v233, 0, 1
	v_bfe_i32 v241, v233, 1, 1
	v_and_b32_e32 v48, v48, v199
	v_and_b32_e32 v49, v49, v241
	v_add_f32_e32 v10, v48, v10
	v_add_f32_e32 v10, v49, v10
	v_cvt_pk_bf16_f32 v242, v48, v49
	v_mfma_f32_32x32x16_bf16 v[32:47], v[204:207], v[246:249], v[32:47]
	v_sub_f32_e32 v50, v50, v12
	v_sub_f32_e32 v51, v51, v12
	v_exp_f32_e32 v50, v50
	v_exp_f32_e32 v51, v51
	v_bfe_i32 v199, v233, 2, 1
	v_bfe_i32 v241, v233, 3, 1
	v_and_b32_e32 v50, v50, v199
	v_and_b32_e32 v51, v51, v241
	v_add_f32_e32 v10, v50, v10
	v_add_f32_e32 v10, v51, v10
	v_cvt_pk_bf16_f32 v243, v50, v51
	v_sub_f32_e32 v52, v52, v12
	v_sub_f32_e32 v53, v53, v12
	v_exp_f32_e32 v52, v52
	v_exp_f32_e32 v53, v53
	v_bfe_i32 v199, v233, 8, 1
	v_bfe_i32 v241, v233, 9, 1
	v_and_b32_e32 v52, v52, v199
	v_and_b32_e32 v53, v53, v241
	v_add_f32_e32 v10, v52, v10
	v_add_f32_e32 v10, v53, v10
	v_cvt_pk_bf16_f32 v244, v52, v53
	v_mfma_f32_32x32x16_bf16 v[16:31], v[220:223], v[246:249], v[16:31]
	v_sub_f32_e32 v54, v54, v12
	v_sub_f32_e32 v55, v55, v12
	v_exp_f32_e32 v54, v54
	v_exp_f32_e32 v55, v55
	v_bfe_i32 v199, v233, 10, 1
	v_bfe_i32 v241, v233, 11, 1
	v_and_b32_e32 v54, v54, v199
	v_and_b32_e32 v55, v55, v241
	v_add_f32_e32 v10, v54, v10
	v_add_f32_e32 v10, v55, v10
	v_cvt_pk_bf16_f32 v245, v54, v55
	v_sub_f32_e32 v56, v56, v12
	v_sub_f32_e32 v57, v57, v12
	v_exp_f32_e32 v56, v56
	v_exp_f32_e32 v57, v57
	v_bfe_i32 v199, v233, 16, 1
	v_bfe_i32 v241, v233, 17, 1
	v_and_b32_e32 v56, v56, v199
	v_and_b32_e32 v57, v57, v241
	v_add_f32_e32 v10, v56, v10
	v_add_f32_e32 v10, v57, v10
	v_cvt_pk_bf16_f32 v246, v56, v57
	v_mfma_f32_32x32x16_bf16 v[32:47], v[208:211], v[242:245], v[32:47]
	v_sub_f32_e32 v58, v58, v12
	v_sub_f32_e32 v59, v59, v12
	v_exp_f32_e32 v58, v58
	v_exp_f32_e32 v59, v59
	v_bfe_i32 v199, v233, 18, 1
	v_bfe_i32 v241, v233, 19, 1
	v_and_b32_e32 v58, v58, v199
	v_and_b32_e32 v59, v59, v241
	v_add_f32_e32 v10, v58, v10
	v_add_f32_e32 v10, v59, v10
	v_cvt_pk_bf16_f32 v247, v58, v59
	v_sub_f32_e32 v60, v60, v12
	v_sub_f32_e32 v61, v61, v12
	v_exp_f32_e32 v60, v60
	v_exp_f32_e32 v61, v61
	v_bfe_i32 v199, v233, 24, 1
	v_bfe_i32 v241, v233, 25, 1
	v_and_b32_e32 v60, v60, v199
	v_and_b32_e32 v61, v61, v241
	v_add_f32_e32 v10, v60, v10
	v_add_f32_e32 v10, v61, v10
	v_cvt_pk_bf16_f32 v248, v60, v61
	v_mfma_f32_32x32x16_bf16 v[16:31], v[224:227], v[242:245], v[16:31]
	v_sub_f32_e32 v62, v62, v12
	v_sub_f32_e32 v63, v63, v12
	v_exp_f32_e32 v62, v62
	v_exp_f32_e32 v63, v63
	v_bfe_i32 v199, v233, 26, 1
	v_bfe_i32 v241, v233, 27, 1
	v_and_b32_e32 v62, v62, v199
	v_and_b32_e32 v63, v63, v241
	v_add_f32_e32 v10, v62, v10
	v_add_f32_e32 v10, v63, v10
	v_cvt_pk_bf16_f32 v249, v62, v63
	v_cmp_eq_u32_e32 vcc, s36, v133
	v_add_u32_e32 v132, 8, v132
	v_fmac_f32_e32 v10, v134, v250
	v_mfma_f32_32x32x16_bf16 v[32:47], v[212:215], v[246:249], v[32:47]
	s_or_b64 s[20:21], vcc, s[20:21]
	s_mov_b32 s37, s36
	v_mov_b32_e32 v135, v12
	v_mov_b32_e32 v134, v10
	s_barrier
	v_mfma_f32_32x32x16_bf16 v[16:31], v[228:231], v[246:249], v[16:31]
	s_waitcnt vmcnt(0)
	v_mov_b64_e32 v[48:49], v[100:101]
	v_mov_b64_e32 v[52:53], v[96:97]
	v_mov_b64_e32 v[50:51], v[102:103]
	v_mov_b64_e32 v[54:55], v[98:99]
	v_mov_b64_e32 v[102:103], v[4:5]
	v_mov_b64_e32 v[98:99], v[8:9]
	v_mov_b64_e32 v[100:101], v[2:3]
	v_mov_b64_e32 v[96:97], v[6:7]
	s_andn2_b64 exec, exec, s[20:21]
	s_cbranch_execz .LBB0_906
	s_branch .LBB0_902

	.amdhsa_kernel _Z14fwd_megakernel6Params
		.amdhsa_group_segment_fixed_size 163840
		.amdhsa_private_segment_fixed_size 0
		.amdhsa_kernarg_size 360
		.amdhsa_user_sgpr_count 2
		.amdhsa_user_sgpr_dispatch_ptr 0
		.amdhsa_user_sgpr_queue_ptr 0
		.amdhsa_user_sgpr_kernarg_segment_ptr 1
		.amdhsa_user_sgpr_dispatch_id 0
		.amdhsa_user_sgpr_kernarg_preload_length 0
		.amdhsa_user_sgpr_kernarg_preload_offset 0
		.amdhsa_user_sgpr_private_segment_size 0
		.amdhsa_uses_dynamic_stack 0
		.amdhsa_enable_private_segment 0
		.amdhsa_system_sgpr_workgroup_id_x 1
		.amdhsa_system_sgpr_workgroup_id_y 0
		.amdhsa_system_sgpr_workgroup_id_z 0
		.amdhsa_system_sgpr_workgroup_info 0
		.amdhsa_system_vgpr_workitem_id 2
		.amdhsa_next_free_vgpr 256
		.amdhsa_next_free_sgpr 98
		.amdhsa_accum_offset 256
		.amdhsa_reserve_vcc 1
		.amdhsa_float_round_mode_32 0
		.amdhsa_float_round_mode_16_64 0
		.amdhsa_float_denorm_mode_32 3
		.amdhsa_float_denorm_mode_16_64 3
		.amdhsa_dx10_clamp 1
		.amdhsa_ieee_mode 1
		.amdhsa_fp16_overflow 0
		.amdhsa_tg_split 0
		.amdhsa_exception_fp_ieee_invalid_op 0
		.amdhsa_exception_fp_denorm_src 0
		.amdhsa_exception_fp_ieee_div_zero 0
		.amdhsa_exception_fp_ieee_overflow 0
		.amdhsa_exception_fp_ieee_underflow 0
		.amdhsa_exception_fp_ieee_inexact 0
		.amdhsa_exception_int_div_zero 0
	.end_amdhsa_kernel

amdhsa.kernels:
  - .agpr_count:     0
    .args:
      - .offset:         0
        .size:           104
        .value_kind:     by_value
      - .offset:         104
        .size:           4
        .value_kind:     hidden_block_count_x
      - .offset:         108
        .size:           4
        .value_kind:     hidden_block_count_y
      - .offset:         112
        .size:           4
        .value_kind:     hidden_block_count_z
      - .offset:         116
        .size:           2
        .value_kind:     hidden_group_size_x
      - .offset:         118
        .size:           2
        .value_kind:     hidden_group_size_y
      - .offset:         120
        .size:           2
        .value_kind:     hidden_group_size_z
      - .offset:         122
        .size:           2
        .value_kind:     hidden_remainder_x
      - .offset:         124
        .size:           2
        .value_kind:     hidden_remainder_y
      - .offset:         126
        .size:           2
        .value_kind:     hidden_remainder_z
      - .offset:         144
        .size:           8
        .value_kind:     hidden_global_offset_x
      - .offset:         152
        .size:           8
        .value_kind:     hidden_global_offset_y
      - .offset:         160
        .size:           8
        .value_kind:     hidden_global_offset_z
      - .offset:         168
        .size:           2
        .value_kind:     hidden_grid_dims
      - .offset:         192
        .size:           8
        .value_kind:     hidden_multigrid_sync_arg
    .group_segment_fixed_size: 163840
    .kernarg_segment_align: 8
    .kernarg_segment_size: 360
    .language:       OpenCL C
    .language_version:
      - 2
      - 0
    .max_flat_workgroup_size: 512
    .name:           _Z14fwd_megakernel6Params
    .private_segment_fixed_size: 0
    .sgpr_count:     104
    .sgpr_spill_count: 379
    .symbol:         _Z14fwd_megakernel6Params.kd
    .uniform_work_group_size: 1
    .uses_dynamic_stack: false
    .vgpr_count:     256
    .vgpr_spill_count: 0
    .wavefront_size: 64
